# Q/O projection small_gemm units: same 8 rows x 128 B load shape + per-wave LDS transpose
# baseline (speedup 1.0000x reference)
.LBB0_76:
	s_ashr_i32 s22, s19, 31
	s_lshr_b32 s22, s22, 28
	s_add_i32 s22, s19, s22
	s_ashr_i32 s22, s22, 4
	s_lshl_b32 s24, s22, 5
	s_lshl_b32 s22, s22, 10
	s_sub_i32 s23, s2, s22
	s_add_i32 s22, s24, 0x4000
	v_or_b32_e32 v2, s22, v176
	v_ashrrev_i32_e32 v3, 31, v2
	v_lshlrev_b64 v[2:3], 11, v[2:3]
	v_lshl_add_u64 v[42:43], v[38:39], 0, v[2:3]
	v_add_co_u32_e32 v72, vcc, s93, v42
	v_add_u32_e32 v14, s23, v176
	s_nop 0
	v_addc_co_u32_e32 v73, vcc, 0, v43, vcc
	v_add_u32_e32 v10, 16, v14
	v_add_u32_e32 v16, 32, v14
	v_add_u32_e32 v22, 48, v14
	v_ashrrev_i32_e32 v15, 31, v14
	v_ashrrev_i32_e32 v11, 31, v10
	v_ashrrev_i32_e32 v17, 31, v16
	v_ashrrev_i32_e32 v23, 31, v22
	v_lshlrev_b64 v[6:7], 11, v[14:15]
	v_lshlrev_b64 v[10:11], 11, v[10:11]
	v_lshlrev_b64 v[14:15], 11, v[16:17]
	v_lshlrev_b64 v[22:23], 11, v[22:23]
	v_lshl_add_u64 v[64:65], v[40:41], 0, v[6:7]
	v_lshl_add_u64 v[66:67], v[40:41], 0, v[10:11]
	v_lshl_add_u64 v[68:69], v[40:41], 0, v[14:15]
	v_lshl_add_u64 v[70:71], v[40:41], 0, v[22:23]
	v_and_b32_e32 v250, 63, v204
	v_readfirstlane_b32 s98, v204
	s_lshr_b32 s98, s98, 6
	s_mul_i32 s98, s98, 0x3600
	v_and_b32_e32 v251, 15, v250
	v_lshrrev_b32_e32 v252, 4, v250
	v_mul_u32_u24_e32 v253, 0x90, v251
	v_lshl_add_u32 v253, v252, 4, v253
	v_add_u32_e32 v253, s98, v253
	v_lshrrev_b32_e32 v34, 3, v250
	v_and_b32_e32 v35, 7, v250
	v_sub_u32_e32 v36, v34, v251
	v_sub_u32_e32 v37, v35, v252
	v_lshlrev_b32_e32 v36, 11, v36
	v_lshl_add_u32 v36, v37, 4, v36
	v_ashrrev_i32_e32 v37, 31, v36
	v_mul_u32_u24_e32 v252, 0x90, v34
	v_lshl_add_u32 v252, v35, 4, v252
	v_add_u32_e32 v252, s98, v252
	v_lshl_add_u64 v[6:7], v[42:43], 0, v[36:37]
	v_add_co_u32_e32 v8, vcc, 0x4000, v6
	s_nop 1
	v_addc_co_u32_e32 v9, vcc, 0, v7, vcc
	v_lshl_add_u64 v[10:11], v[72:73], 0, v[36:37]
	v_add_co_u32_e32 v12, vcc, 0x4000, v10
	s_nop 1
	v_addc_co_u32_e32 v13, vcc, 0, v11, vcc
	v_lshl_add_u64 v[14:15], v[64:65], 0, v[36:37]
	v_add_co_u32_e32 v16, vcc, 0x4000, v14
	s_nop 1
	v_addc_co_u32_e32 v17, vcc, 0, v15, vcc
	v_lshl_add_u64 v[18:19], v[66:67], 0, v[36:37]
	v_add_co_u32_e32 v20, vcc, 0x4000, v18
	s_nop 1
	v_addc_co_u32_e32 v21, vcc, 0, v19, vcc
	v_lshl_add_u64 v[22:23], v[68:69], 0, v[36:37]
	v_add_co_u32_e32 v24, vcc, 0x4000, v22
	s_nop 1
	v_addc_co_u32_e32 v25, vcc, 0, v23, vcc
	v_lshl_add_u64 v[26:27], v[70:71], 0, v[36:37]
	v_add_co_u32_e32 v28, vcc, 0x4000, v26
	s_nop 1
	v_addc_co_u32_e32 v29, vcc, 0, v27, vcc
	global_load_dwordx4 v[74:77], v[6:7], off
	global_load_dwordx4 v[82:85], v[8:9], off
	global_load_dwordx4 v[90:93], v[10:11], off
	global_load_dwordx4 v[98:101], v[12:13], off
	global_load_dwordx4 v[106:109], v[14:15], off
	global_load_dwordx4 v[114:117], v[16:17], off
	global_load_dwordx4 v[122:125], v[18:19], off
	global_load_dwordx4 v[130:133], v[20:21], off
	global_load_dwordx4 v[162:165], v[22:23], off
	global_load_dwordx4 v[170:173], v[24:25], off
	global_load_dwordx4 v[182:185], v[26:27], off
	global_load_dwordx4 v[210:213], v[28:29], off
	global_load_dwordx4 v[78:81], v[6:7], off offset:128
	global_load_dwordx4 v[86:89], v[8:9], off offset:128
	global_load_dwordx4 v[94:97], v[10:11], off offset:128
	global_load_dwordx4 v[102:105], v[12:13], off offset:128
	global_load_dwordx4 v[110:113], v[14:15], off offset:128
	global_load_dwordx4 v[118:121], v[16:17], off offset:128
	global_load_dwordx4 v[126:129], v[18:19], off offset:128
	global_load_dwordx4 v[134:137], v[20:21], off offset:128
	global_load_dwordx4 v[166:169], v[22:23], off offset:128
	global_load_dwordx4 v[178:181], v[24:25], off offset:128
	global_load_dwordx4 v[206:209], v[26:27], off offset:128
	global_load_dwordx4 v[214:217], v[28:29], off offset:128
	v_add_u32_e32 v42, s23, v44
	v_ashrrev_i32_e32 v43, 31, v42
	s_waitcnt vmcnt(12)
	s_barrier
	ds_write_b128 v252, v[74:77]
	ds_write_b128 v252, v[82:85] offset:1152
	ds_write_b128 v252, v[90:93] offset:2304
	ds_write_b128 v252, v[98:101] offset:3456
	ds_write_b128 v252, v[106:109] offset:4608
	ds_write_b128 v252, v[114:117] offset:5760
	ds_write_b128 v252, v[122:125] offset:6912
	ds_write_b128 v252, v[130:133] offset:8064
	ds_write_b128 v252, v[162:165] offset:9216
	ds_write_b128 v252, v[170:173] offset:10368
	ds_write_b128 v252, v[182:185] offset:11520
	ds_write_b128 v252, v[210:213] offset:12672
	ds_read_b128 v[48:51], v253
	ds_read_b128 v[56:59], v253 offset:2304
	ds_read_b128 v[218:221], v253 offset:4608
	ds_read_b128 v[226:229], v253 offset:6912
	ds_read_b128 v[234:237], v253 offset:9216
	ds_read_b128 v[242:245], v253 offset:11520
	ds_read_b128 v[52:55], v253 offset:64
	ds_read_b128 v[60:63], v253 offset:2368
	ds_read_b128 v[222:225], v253 offset:4672
	ds_read_b128 v[230:233], v253 offset:6976
	ds_read_b128 v[238:241], v253 offset:9280
	ds_read_b128 v[246:249], v253 offset:11584
	s_waitcnt lgkmcnt(6)
	v_mfma_f32_16x16x32_bf16 v[2:5], v[48:51], v[218:221], 0
	v_mfma_f32_16x16x32_bf16 v[6:9], v[48:51], v[226:229], 0
	v_mfma_f32_16x16x32_bf16 v[10:13], v[48:51], v[234:237], 0
	v_mfma_f32_16x16x32_bf16 v[14:17], v[48:51], v[242:245], 0
	v_mfma_f32_16x16x32_bf16 v[18:21], v[56:59], v[218:221], 0
	v_mfma_f32_16x16x32_bf16 v[22:25], v[56:59], v[226:229], 0
	v_mfma_f32_16x16x32_bf16 v[26:29], v[56:59], v[234:237], 0
	v_mfma_f32_16x16x32_bf16 v[30:33], v[56:59], v[242:245], 0
	s_waitcnt lgkmcnt(0)
	v_mfma_f32_16x16x32_bf16 v[2:5], v[52:55], v[222:225], v[2:5]
	v_mfma_f32_16x16x32_bf16 v[6:9], v[52:55], v[230:233], v[6:9]
	v_mfma_f32_16x16x32_bf16 v[10:13], v[52:55], v[238:241], v[10:13]
	v_mfma_f32_16x16x32_bf16 v[14:17], v[52:55], v[246:249], v[14:17]
	v_mfma_f32_16x16x32_bf16 v[18:21], v[60:63], v[222:225], v[18:21]
	v_mfma_f32_16x16x32_bf16 v[22:25], v[60:63], v[230:233], v[22:25]
	v_mfma_f32_16x16x32_bf16 v[26:29], v[60:63], v[238:241], v[26:29]
	v_mfma_f32_16x16x32_bf16 v[30:33], v[60:63], v[246:249], v[30:33]
	s_waitcnt vmcnt(0)
	ds_write_b128 v252, v[78:81]
	ds_write_b128 v252, v[86:89] offset:1152
	ds_write_b128 v252, v[94:97] offset:2304
	ds_write_b128 v252, v[102:105] offset:3456
	ds_write_b128 v252, v[110:113] offset:4608
	ds_write_b128 v252, v[118:121] offset:5760
	ds_write_b128 v252, v[126:129] offset:6912
	ds_write_b128 v252, v[134:137] offset:8064
	ds_write_b128 v252, v[166:169] offset:9216
	ds_write_b128 v252, v[178:181] offset:10368
	ds_write_b128 v252, v[206:209] offset:11520
	ds_write_b128 v252, v[214:217] offset:12672
	ds_read_b128 v[48:51], v253
	ds_read_b128 v[56:59], v253 offset:2304
	ds_read_b128 v[218:221], v253 offset:4608
	ds_read_b128 v[226:229], v253 offset:6912
	ds_read_b128 v[234:237], v253 offset:9216
	ds_read_b128 v[242:245], v253 offset:11520
	ds_read_b128 v[52:55], v253 offset:64
	ds_read_b128 v[60:63], v253 offset:2368
	ds_read_b128 v[222:225], v253 offset:4672
	ds_read_b128 v[230:233], v253 offset:6976
	ds_read_b128 v[238:241], v253 offset:9280
	ds_read_b128 v[246:249], v253 offset:11584
	s_waitcnt lgkmcnt(6)
	v_mfma_f32_16x16x32_bf16 v[2:5], v[48:51], v[218:221], v[2:5]
	v_mfma_f32_16x16x32_bf16 v[6:9], v[48:51], v[226:229], v[6:9]
	v_mfma_f32_16x16x32_bf16 v[10:13], v[48:51], v[234:237], v[10:13]
	v_mfma_f32_16x16x32_bf16 v[14:17], v[48:51], v[242:245], v[14:17]
	v_mfma_f32_16x16x32_bf16 v[18:21], v[56:59], v[218:221], v[18:21]
	v_mfma_f32_16x16x32_bf16 v[22:25], v[56:59], v[226:229], v[22:25]
	v_mfma_f32_16x16x32_bf16 v[26:29], v[56:59], v[234:237], v[26:29]
	v_mfma_f32_16x16x32_bf16 v[30:33], v[56:59], v[242:245], v[30:33]
	s_waitcnt lgkmcnt(0)
	v_mfma_f32_16x16x32_bf16 v[2:5], v[52:55], v[222:225], v[2:5]
	v_mfma_f32_16x16x32_bf16 v[6:9], v[52:55], v[230:233], v[6:9]
	v_mfma_f32_16x16x32_bf16 v[10:13], v[52:55], v[238:241], v[10:13]
	v_mfma_f32_16x16x32_bf16 v[14:17], v[52:55], v[246:249], v[14:17]
	v_mfma_f32_16x16x32_bf16 v[18:21], v[60:63], v[222:225], v[18:21]
	v_mfma_f32_16x16x32_bf16 v[22:25], v[60:63], v[230:233], v[22:25]
	v_mfma_f32_16x16x32_bf16 v[26:29], v[60:63], v[238:241], v[26:29]
	v_mfma_f32_16x16x32_bf16 v[30:33], v[60:63], v[246:249], v[30:33]
	s_waitcnt lgkmcnt(0)
	s_barrier
	s_nop 7
	s_nop 7
	v_add_u32_e32 v34, 0x1000, v45
	v_add_u32_e32 v35, 0x1400, v45
	ds_write2_b32 v45, v2, v6 offset1:16
	ds_write2_b32 v45, v3, v7 offset0:68 offset1:84
	ds_write2_b32 v45, v4, v8 offset0:136 offset1:152
	ds_write2_b32 v45, v5, v9 offset0:204 offset1:220
	ds_write2_b32 v45, v10, v14 offset0:32 offset1:48
	ds_write2_b32 v45, v11, v15 offset0:100 offset1:116
	ds_write2_b32 v45, v12, v16 offset0:168 offset1:184
	ds_write2_b32 v45, v13, v17 offset0:236 offset1:252
	ds_write2_b32 v34, v18, v22 offset0:64 offset1:80
	ds_write2_b32 v34, v19, v23 offset0:132 offset1:148
	ds_write2_b32 v34, v20, v24 offset0:200 offset1:216
	ds_write2_b32 v35, v21, v25 offset0:12 offset1:28
	ds_write2_b32 v34, v26, v30 offset0:96 offset1:112
	ds_write2_b32 v34, v27, v31 offset0:164 offset1:180
	ds_write2_b32 v34, v28, v32 offset0:232 offset1:248
	ds_write2_b32 v35, v29, v33 offset0:44 offset1:60
	s_andn2_b64 vcc, exec, s[0:1]
	s_waitcnt lgkmcnt(0)
	s_barrier
	ds_read_b128 v[34:37], v46
	ds_read_b128 v[30:33], v46 offset:8704
	ds_read_b128 v[26:29], v46 offset:17408
	ds_read_b128 v[22:25], v46 offset:26112
	ds_read_b128 v[18:21], v46 offset:34816
	ds_read_b128 v[10:13], v46 offset:43520
	ds_read_b128 v[6:9], v46 offset:52224
	ds_read_b128 v[2:5], v46 offset:60928
	s_cbranch_vccz .LBB0_74
	v_mov_b32_e32 v14, 0
	v_mov_b32_e32 v15, v14
	v_mov_b32_e32 v16, v14
	v_mov_b32_e32 v17, v14
	s_branch .LBB0_75

.LBB0_276:
	s_ashr_i32 s19, s17, 31
	s_lshr_b32 s19, s19, 28
	s_add_i32 s19, s17, s19
	s_ashr_i32 s19, s19, 4
	s_lshl_b32 s23, s19, 5
	s_lshl_b32 s19, s19, 10
	s_sub_i32 s22, s2, s19
	s_add_i32 s19, s23, 0x4000
	v_or_b32_e32 v2, s19, v176
	v_ashrrev_i32_e32 v3, 31, v2
	v_lshlrev_b64 v[2:3], 11, v[2:3]
	v_lshl_add_u64 v[42:43], v[38:39], 0, v[2:3]
	v_add_co_u32_e32 v72, vcc, s93, v42
	v_add_u32_e32 v14, s22, v176
	s_nop 0
	v_addc_co_u32_e32 v73, vcc, 0, v43, vcc
	v_add_u32_e32 v10, 16, v14
	v_add_u32_e32 v16, 32, v14
	v_add_u32_e32 v22, 48, v14
	v_ashrrev_i32_e32 v15, 31, v14
	v_ashrrev_i32_e32 v11, 31, v10
	v_ashrrev_i32_e32 v17, 31, v16
	v_ashrrev_i32_e32 v23, 31, v22
	v_lshlrev_b64 v[6:7], 11, v[14:15]
	v_lshlrev_b64 v[10:11], 11, v[10:11]
	v_lshlrev_b64 v[14:15], 11, v[16:17]
	v_lshlrev_b64 v[22:23], 11, v[22:23]
	v_lshl_add_u64 v[64:65], v[40:41], 0, v[6:7]
	v_lshl_add_u64 v[66:67], v[40:41], 0, v[10:11]
	v_lshl_add_u64 v[68:69], v[40:41], 0, v[14:15]
	v_lshl_add_u64 v[70:71], v[40:41], 0, v[22:23]
	v_and_b32_e32 v250, 63, v204
	v_readfirstlane_b32 s98, v204
	s_lshr_b32 s98, s98, 6
	s_mul_i32 s98, s98, 0x3600
	v_and_b32_e32 v251, 15, v250
	v_lshrrev_b32_e32 v252, 4, v250
	v_mul_u32_u24_e32 v253, 0x90, v251
	v_lshl_add_u32 v253, v252, 4, v253
	v_add_u32_e32 v253, s98, v253
	v_lshrrev_b32_e32 v34, 3, v250
	v_and_b32_e32 v35, 7, v250
	v_sub_u32_e32 v36, v34, v251
	v_sub_u32_e32 v37, v35, v252
	v_lshlrev_b32_e32 v36, 11, v36
	v_lshl_add_u32 v36, v37, 4, v36
	v_ashrrev_i32_e32 v37, 31, v36
	v_mul_u32_u24_e32 v252, 0x90, v34
	v_lshl_add_u32 v252, v35, 4, v252
	v_add_u32_e32 v252, s98, v252
	v_lshl_add_u64 v[6:7], v[42:43], 0, v[36:37]
	v_add_co_u32_e32 v8, vcc, 0x4000, v6
	s_nop 1
	v_addc_co_u32_e32 v9, vcc, 0, v7, vcc
	v_lshl_add_u64 v[10:11], v[72:73], 0, v[36:37]
	v_add_co_u32_e32 v12, vcc, 0x4000, v10
	s_nop 1
	v_addc_co_u32_e32 v13, vcc, 0, v11, vcc
	v_lshl_add_u64 v[14:15], v[64:65], 0, v[36:37]
	v_add_co_u32_e32 v16, vcc, 0x4000, v14
	s_nop 1
	v_addc_co_u32_e32 v17, vcc, 0, v15, vcc
	v_lshl_add_u64 v[18:19], v[66:67], 0, v[36:37]
	v_add_co_u32_e32 v20, vcc, 0x4000, v18
	s_nop 1
	v_addc_co_u32_e32 v21, vcc, 0, v19, vcc
	v_lshl_add_u64 v[22:23], v[68:69], 0, v[36:37]
	v_add_co_u32_e32 v24, vcc, 0x4000, v22
	s_nop 1
	v_addc_co_u32_e32 v25, vcc, 0, v23, vcc
	v_lshl_add_u64 v[26:27], v[70:71], 0, v[36:37]
	v_add_co_u32_e32 v28, vcc, 0x4000, v26
	s_nop 1
	v_addc_co_u32_e32 v29, vcc, 0, v27, vcc
	global_load_dwordx4 v[74:77], v[6:7], off
	global_load_dwordx4 v[82:85], v[8:9], off
	global_load_dwordx4 v[90:93], v[10:11], off
	global_load_dwordx4 v[98:101], v[12:13], off
	global_load_dwordx4 v[106:109], v[14:15], off
	global_load_dwordx4 v[114:117], v[16:17], off
	global_load_dwordx4 v[122:125], v[18:19], off
	global_load_dwordx4 v[130:133], v[20:21], off
	global_load_dwordx4 v[162:165], v[22:23], off
	global_load_dwordx4 v[170:173], v[24:25], off
	global_load_dwordx4 v[182:185], v[26:27], off
	global_load_dwordx4 v[210:213], v[28:29], off
	global_load_dwordx4 v[78:81], v[6:7], off offset:128
	global_load_dwordx4 v[86:89], v[8:9], off offset:128
	global_load_dwordx4 v[94:97], v[10:11], off offset:128
	global_load_dwordx4 v[102:105], v[12:13], off offset:128
	global_load_dwordx4 v[110:113], v[14:15], off offset:128
	global_load_dwordx4 v[118:121], v[16:17], off offset:128
	global_load_dwordx4 v[126:129], v[18:19], off offset:128
	global_load_dwordx4 v[134:137], v[20:21], off offset:128
	global_load_dwordx4 v[166:169], v[22:23], off offset:128
	global_load_dwordx4 v[178:181], v[24:25], off offset:128
	global_load_dwordx4 v[206:209], v[26:27], off offset:128
	global_load_dwordx4 v[214:217], v[28:29], off offset:128
	v_add_u32_e32 v42, s22, v44
	v_ashrrev_i32_e32 v43, 31, v42
	s_waitcnt vmcnt(12)
	s_barrier
	ds_write_b128 v252, v[74:77]
	ds_write_b128 v252, v[82:85] offset:1152
	ds_write_b128 v252, v[90:93] offset:2304
	ds_write_b128 v252, v[98:101] offset:3456
	ds_write_b128 v252, v[106:109] offset:4608
	ds_write_b128 v252, v[114:117] offset:5760
	ds_write_b128 v252, v[122:125] offset:6912
	ds_write_b128 v252, v[130:133] offset:8064
	ds_write_b128 v252, v[162:165] offset:9216
	ds_write_b128 v252, v[170:173] offset:10368
	ds_write_b128 v252, v[182:185] offset:11520
	ds_write_b128 v252, v[210:213] offset:12672
	ds_read_b128 v[48:51], v253
	ds_read_b128 v[56:59], v253 offset:2304
	ds_read_b128 v[218:221], v253 offset:4608
	ds_read_b128 v[226:229], v253 offset:6912
	ds_read_b128 v[234:237], v253 offset:9216
	ds_read_b128 v[242:245], v253 offset:11520
	ds_read_b128 v[52:55], v253 offset:64
	ds_read_b128 v[60:63], v253 offset:2368
	ds_read_b128 v[222:225], v253 offset:4672
	ds_read_b128 v[230:233], v253 offset:6976
	ds_read_b128 v[238:241], v253 offset:9280
	ds_read_b128 v[246:249], v253 offset:11584
	s_waitcnt lgkmcnt(6)
	v_mfma_f32_16x16x32_bf16 v[2:5], v[48:51], v[218:221], 0
	v_mfma_f32_16x16x32_bf16 v[6:9], v[48:51], v[226:229], 0
	v_mfma_f32_16x16x32_bf16 v[10:13], v[48:51], v[234:237], 0
	v_mfma_f32_16x16x32_bf16 v[14:17], v[48:51], v[242:245], 0
	v_mfma_f32_16x16x32_bf16 v[18:21], v[56:59], v[218:221], 0
	v_mfma_f32_16x16x32_bf16 v[22:25], v[56:59], v[226:229], 0
	v_mfma_f32_16x16x32_bf16 v[26:29], v[56:59], v[234:237], 0
	v_mfma_f32_16x16x32_bf16 v[30:33], v[56:59], v[242:245], 0
	s_waitcnt lgkmcnt(0)
	v_mfma_f32_16x16x32_bf16 v[2:5], v[52:55], v[222:225], v[2:5]
	v_mfma_f32_16x16x32_bf16 v[6:9], v[52:55], v[230:233], v[6:9]
	v_mfma_f32_16x16x32_bf16 v[10:13], v[52:55], v[238:241], v[10:13]
	v_mfma_f32_16x16x32_bf16 v[14:17], v[52:55], v[246:249], v[14:17]
	v_mfma_f32_16x16x32_bf16 v[18:21], v[60:63], v[222:225], v[18:21]
	v_mfma_f32_16x16x32_bf16 v[22:25], v[60:63], v[230:233], v[22:25]
	v_mfma_f32_16x16x32_bf16 v[26:29], v[60:63], v[238:241], v[26:29]
	v_mfma_f32_16x16x32_bf16 v[30:33], v[60:63], v[246:249], v[30:33]
	s_waitcnt vmcnt(0)
	ds_write_b128 v252, v[78:81]
	ds_write_b128 v252, v[86:89] offset:1152
	ds_write_b128 v252, v[94:97] offset:2304
	ds_write_b128 v252, v[102:105] offset:3456
	ds_write_b128 v252, v[110:113] offset:4608
	ds_write_b128 v252, v[118:121] offset:5760
	ds_write_b128 v252, v[126:129] offset:6912
	ds_write_b128 v252, v[134:137] offset:8064
	ds_write_b128 v252, v[166:169] offset:9216
	ds_write_b128 v252, v[178:181] offset:10368
	ds_write_b128 v252, v[206:209] offset:11520
	ds_write_b128 v252, v[214:217] offset:12672
	ds_read_b128 v[48:51], v253
	ds_read_b128 v[56:59], v253 offset:2304
	ds_read_b128 v[218:221], v253 offset:4608
	ds_read_b128 v[226:229], v253 offset:6912
	ds_read_b128 v[234:237], v253 offset:9216
	ds_read_b128 v[242:245], v253 offset:11520
	ds_read_b128 v[52:55], v253 offset:64
	ds_read_b128 v[60:63], v253 offset:2368
	ds_read_b128 v[222:225], v253 offset:4672
	ds_read_b128 v[230:233], v253 offset:6976
	ds_read_b128 v[238:241], v253 offset:9280
	ds_read_b128 v[246:249], v253 offset:11584
	s_waitcnt lgkmcnt(6)
	v_mfma_f32_16x16x32_bf16 v[2:5], v[48:51], v[218:221], v[2:5]
	v_mfma_f32_16x16x32_bf16 v[6:9], v[48:51], v[226:229], v[6:9]
	v_mfma_f32_16x16x32_bf16 v[10:13], v[48:51], v[234:237], v[10:13]
	v_mfma_f32_16x16x32_bf16 v[14:17], v[48:51], v[242:245], v[14:17]
	v_mfma_f32_16x16x32_bf16 v[18:21], v[56:59], v[218:221], v[18:21]
	v_mfma_f32_16x16x32_bf16 v[22:25], v[56:59], v[226:229], v[22:25]
	v_mfma_f32_16x16x32_bf16 v[26:29], v[56:59], v[234:237], v[26:29]
	v_mfma_f32_16x16x32_bf16 v[30:33], v[56:59], v[242:245], v[30:33]
	s_waitcnt lgkmcnt(0)
	v_mfma_f32_16x16x32_bf16 v[2:5], v[52:55], v[222:225], v[2:5]
	v_mfma_f32_16x16x32_bf16 v[6:9], v[52:55], v[230:233], v[6:9]
	v_mfma_f32_16x16x32_bf16 v[10:13], v[52:55], v[238:241], v[10:13]
	v_mfma_f32_16x16x32_bf16 v[14:17], v[52:55], v[246:249], v[14:17]
	v_mfma_f32_16x16x32_bf16 v[18:21], v[60:63], v[222:225], v[18:21]
	v_mfma_f32_16x16x32_bf16 v[22:25], v[60:63], v[230:233], v[22:25]
	v_mfma_f32_16x16x32_bf16 v[26:29], v[60:63], v[238:241], v[26:29]
	v_mfma_f32_16x16x32_bf16 v[30:33], v[60:63], v[246:249], v[30:33]
	s_waitcnt lgkmcnt(0)
	s_barrier
	s_nop 7
	s_nop 7
	v_add_u32_e32 v34, 0x1000, v45
	v_add_u32_e32 v35, 0x1400, v45
	ds_write2_b32 v45, v2, v6 offset1:16
	ds_write2_b32 v45, v3, v7 offset0:68 offset1:84
	ds_write2_b32 v45, v4, v8 offset0:136 offset1:152
	ds_write2_b32 v45, v5, v9 offset0:204 offset1:220
	ds_write2_b32 v45, v10, v14 offset0:32 offset1:48
	ds_write2_b32 v45, v11, v15 offset0:100 offset1:116
	ds_write2_b32 v45, v12, v16 offset0:168 offset1:184
	ds_write2_b32 v45, v13, v17 offset0:236 offset1:252
	ds_write2_b32 v34, v18, v22 offset0:64 offset1:80
	ds_write2_b32 v34, v19, v23 offset0:132 offset1:148
	ds_write2_b32 v34, v20, v24 offset0:200 offset1:216
	ds_write2_b32 v35, v21, v25 offset0:12 offset1:28
	ds_write2_b32 v34, v26, v30 offset0:96 offset1:112
	ds_write2_b32 v34, v27, v31 offset0:164 offset1:180
	ds_write2_b32 v34, v28, v32 offset0:232 offset1:248
	ds_write2_b32 v35, v29, v33 offset0:44 offset1:60
	s_andn2_b64 vcc, exec, s[0:1]
	s_waitcnt lgkmcnt(0)
	s_barrier
	ds_read_b128 v[34:37], v46
	ds_read_b128 v[30:33], v46 offset:8704
	ds_read_b128 v[26:29], v46 offset:17408
	ds_read_b128 v[22:25], v46 offset:26112
	ds_read_b128 v[18:21], v46 offset:34816
	ds_read_b128 v[10:13], v46 offset:43520
	ds_read_b128 v[6:9], v46 offset:52224
	ds_read_b128 v[2:5], v46 offset:60928
	s_cbranch_vccz .LBB0_274
	v_mov_b32_e32 v14, 0
	v_mov_b32_e32 v15, v14
	v_mov_b32_e32 v16, v14
	v_mov_b32_e32 v17, v14
	s_branch .LBB0_275
